# P16 epilogue: 16 residual loads per tile issued up front, per-step vmcnt(0) waits removed
# speedup vs baseline: 1.0131x; 1.0018x over previous
; __device__ __forceinline__ unsigned pk2(float lo, float hi) { f32x2 v = {lo, hi}; bf16x2_t b = __builtin_convertvector(v, bf16x2_t); return __builtin_bit_cast(unsigned, b); }
;     __device__ __forceinline__ void operator()(const f32x4 (&acc)[2][2][4][2], const Unit& u, int wr, int wc, int fr, int fq) const {
;     ...
;         for (int bj = 0; bj < 2; ++bj) { const int c = col0 + bj * HALF;
;             const f32x4 g0 = *(const f32x4*)(gp + c), g1 = *(const f32x4*)(gp + c + 4);
;             const f32x4 b0 = bias ? *(const f32x4*)(bias + c) : (f32x4){0.f, 0.f, 0.f, 0.f}, b1 = bias ? *(const f32x4*)(bias + c + 4) : (f32x4){0.f, 0.f, 0.f, 0.f};
; #pragma unroll
;             for (int ai = 0; ai < 2; ++ai)
; #pragma unroll
;                 for (int m = 0; m < 4; ++m) { const size_t off = (size_t)(row0 + ai * HALF + m * 16) * 1024 + c;
;                     f32x4 x0, x1;
;                     if (BASE_BF16) { const u32x4 v = *(const u32x4*)((const bf16_t*)base + off);
;                         x0 = (f32x4){__uint_as_float(v.x << 16), __uint_as_float(v.x & 0xffff0000u), __uint_as_float(v.y << 16), __uint_as_float(v.y & 0xffff0000u)};
;                         x1 = (f32x4){__uint_as_float(v.z << 16), __uint_as_float(v.z & 0xffff0000u), __uint_as_float(v.w << 16), __uint_as_float(v.w & 0xffff0000u)}; }
;                     else { x0 = *(const f32x4*)((const float*)base + off); x1 = *(const f32x4*)((const float*)base + off + 4); }
;                     x0 = x0 + g0 * (acc[ai][bj][m][0] + b0); x1 = x1 + g1 * (acc[ai][bj][m][1] + b1);
;                     if (OUT_BF16) { u32x4 w; w.x = pk2(x0[0], x0[1]); w.y = pk2(x0[2], x0[3]); w.z = pk2(x1[0], x1[1]); w.w = pk2(x1[2], x1[3]); *(u32x4*)((bf16_t*)out + off) = w; }
;                     else { *(f32x4*)((float*)out + off) = x0; *(f32x4*)((float*)out + off + 4) = x1; } } }
.LBB0_1420:
	v_lshl_add_u32 v168, s53, 8, v158
	v_lshl_or_b32 v152, s54, 8, v160
	v_ashrrev_i32_e32 v169, 31, v168
	v_lshlrev_b64 v[156:157], 10, v[168:169]
	v_ashrrev_i32_e32 v153, 31, v152
	s_ashr_i32 s24, s53, 5
	v_lshl_add_u64 v[170:171], v[156:157], 0, v[152:153]
	s_mul_hi_i32 s25, s24, 0x6000
	s_mulk_i32 s24, 0x6000
	v_lshl_add_u64 v[128:129], v[170:171], 1, s[8:9]
	s_add_u32 s24, s44, s24
	global_load_dwordx4 v[184:187], v[128:129], off
	s_mov_b32 s57, 0
	s_mov_b32 s56, 0x8000
	v_lshl_add_u64 v[250:251], v[128:129], 0, s[56:57]
	global_load_dwordx4 v[188:191], v[250:251], off
	s_mov_b32 s56, 0x10000
	v_lshl_add_u64 v[250:251], v[128:129], 0, s[56:57]
	global_load_dwordx4 v[192:195], v[250:251], off
	s_mov_b32 s56, 0x18000
	v_lshl_add_u64 v[250:251], v[128:129], 0, s[56:57]
	global_load_dwordx4 v[196:199], v[250:251], off
	s_mov_b32 s56, 0x40000
	v_lshl_add_u64 v[250:251], v[128:129], 0, s[56:57]
	global_load_dwordx4 v[200:203], v[250:251], off
	s_mov_b32 s56, 0x48000
	v_lshl_add_u64 v[250:251], v[128:129], 0, s[56:57]
	global_load_dwordx4 v[204:207], v[250:251], off
	s_mov_b32 s56, 0x50000
	v_lshl_add_u64 v[250:251], v[128:129], 0, s[56:57]
	global_load_dwordx4 v[208:211], v[250:251], off
	s_mov_b32 s56, 0x58000
	v_lshl_add_u64 v[250:251], v[128:129], 0, s[56:57]
	global_load_dwordx4 v[212:215], v[250:251], off
	s_mov_b32 s56, 0x100
	v_lshl_add_u64 v[250:251], v[128:129], 0, s[56:57]
	global_load_dwordx4 v[216:219], v[250:251], off
	s_mov_b32 s56, 0x8100
	v_lshl_add_u64 v[250:251], v[128:129], 0, s[56:57]
	global_load_dwordx4 v[220:223], v[250:251], off
	s_mov_b32 s56, 0x10100
	v_lshl_add_u64 v[250:251], v[128:129], 0, s[56:57]
	global_load_dwordx4 v[224:227], v[250:251], off
	s_mov_b32 s56, 0x18100
	v_lshl_add_u64 v[250:251], v[128:129], 0, s[56:57]
	global_load_dwordx4 v[228:231], v[250:251], off
	s_mov_b32 s56, 0x40100
	v_lshl_add_u64 v[250:251], v[128:129], 0, s[56:57]
	global_load_dwordx4 v[232:235], v[250:251], off
	s_mov_b32 s56, 0x48100
	v_lshl_add_u64 v[250:251], v[128:129], 0, s[56:57]
	global_load_dwordx4 v[236:239], v[250:251], off
	s_mov_b32 s56, 0x50100
	v_lshl_add_u64 v[250:251], v[128:129], 0, s[56:57]
	global_load_dwordx4 v[240:243], v[250:251], off
	s_mov_b32 s56, 0x58100
	v_lshl_add_u64 v[250:251], v[128:129], 0, s[56:57]
	global_load_dwordx4 v[244:247], v[250:251], off
	s_addc_u32 s25, s45, s25
	v_lshl_add_u64 v[154:155], v[152:153], 2, s[24:25]
	global_load_dwordx4 v[132:135], v[154:155], off
	global_load_dwordx4 v[128:131], v[154:155], off offset:16
	v_pk_add_f32 v[174:175], v[120:121], 0 op_sel_hi:[1,0]
	v_or_b32_e32 v120, 16, v168
	v_ashrrev_i32_e32 v121, 31, v120
	v_pk_add_f32 v[126:127], v[126:127], 0 op_sel_hi:[1,0]
	v_pk_add_f32 v[124:125], v[124:125], 0 op_sel_hi:[1,0]
	v_pk_add_f32 v[172:173], v[122:123], 0 op_sel_hi:[1,0]
	v_lshlrev_b64 v[122:123], 10, v[120:121]
	v_lshl_add_u64 v[120:121], v[170:171], 2, s[26:27]
	v_lshl_add_u64 v[170:171], v[122:123], 0, v[152:153]
	v_lshl_add_u64 v[176:177], v[170:171], 1, s[8:9]
	v_pk_add_f32 v[118:119], v[118:119], 0 op_sel_hi:[1,0]
	v_pk_add_f32 v[116:117], v[116:117], 0 op_sel_hi:[1,0]
	v_pk_add_f32 v[110:111], v[110:111], 0 op_sel_hi:[1,0]
	v_pk_add_f32 v[108:109], v[108:109], 0 op_sel_hi:[1,0]
	v_pk_add_f32 v[102:103], v[102:103], 0 op_sel_hi:[1,0]
	v_pk_add_f32 v[100:101], v[100:101], 0 op_sel_hi:[1,0]
	v_pk_add_f32 v[94:95], v[94:95], 0 op_sel_hi:[1,0]
	v_pk_add_f32 v[92:93], v[92:93], 0 op_sel_hi:[1,0]
	v_pk_add_f32 v[86:87], v[86:87], 0 op_sel_hi:[1,0]
	v_pk_add_f32 v[84:85], v[84:85], 0 op_sel_hi:[1,0]
	v_pk_add_f32 v[78:79], v[78:79], 0 op_sel_hi:[1,0]
	v_pk_add_f32 v[74:75], v[74:75], 0 op_sel_hi:[1,0]
	v_pk_add_f32 v[70:71], v[70:71], 0 op_sel_hi:[1,0]
	v_pk_add_f32 v[68:69], v[68:69], 0 op_sel_hi:[1,0]
	v_pk_add_f32 v[66:67], v[66:67], 0 op_sel_hi:[1,0]
	v_pk_add_f32 v[64:65], v[64:65], 0 op_sel_hi:[1,0]
	v_pk_add_f32 v[54:55], v[54:55], 0 op_sel_hi:[1,0]
	v_pk_add_f32 v[52:53], v[52:53], 0 op_sel_hi:[1,0]
	v_pk_add_f32 v[46:47], v[46:47], 0 op_sel_hi:[1,0]
	v_pk_add_f32 v[44:45], v[44:45], 0 op_sel_hi:[1,0]
	v_pk_add_f32 v[38:39], v[38:39], 0 op_sel_hi:[1,0]
	v_pk_add_f32 v[36:37], v[36:37], 0 op_sel_hi:[1,0]
	v_pk_add_f32 v[30:31], v[30:31], 0 op_sel_hi:[1,0]
	v_pk_add_f32 v[28:29], v[28:29], 0 op_sel_hi:[1,0]
	v_pk_add_f32 v[22:23], v[22:23], 0 op_sel_hi:[1,0]
	v_pk_add_f32 v[20:21], v[20:21], 0 op_sel_hi:[1,0]
	v_pk_add_f32 v[14:15], v[14:15], 0 op_sel_hi:[1,0]
	v_pk_add_f32 v[12:13], v[12:13], 0 op_sel_hi:[1,0]
	v_pk_add_f32 v[6:7], v[6:7], 0 op_sel_hi:[1,0]
	v_pk_add_f32 v[4:5], v[4:5], 0 op_sel_hi:[1,0]
	s_and_b64 vcc, exec, s[0:1]
	s_mov_b64 s[0:1], -1
	s_waitcnt vmcnt(0)
; __device__ __forceinline__ unsigned pk2(float lo, float hi) { f32x2 v = {lo, hi}; bf16x2_t b = __builtin_convertvector(v, bf16x2_t); return __builtin_bit_cast(unsigned, b); }
;     __device__ __forceinline__ void operator()(const f32x4 (&acc)[2][2][4][2], const Unit& u, int wr, int wc, int fr, int fq) const {
;     ...
;         for (int bj = 0; bj < 2; ++bj) { const int c = col0 + bj * HALF;
;             const f32x4 g0 = *(const f32x4*)(gp + c), g1 = *(const f32x4*)(gp + c + 4);
;             const f32x4 b0 = bias ? *(const f32x4*)(bias + c) : (f32x4){0.f, 0.f, 0.f, 0.f}, b1 = bias ? *(const f32x4*)(bias + c + 4) : (f32x4){0.f, 0.f, 0.f, 0.f};
; #pragma unroll
;             for (int ai = 0; ai < 2; ++ai)
; #pragma unroll
;                 for (int m = 0; m < 4; ++m) { const size_t off = (size_t)(row0 + ai * HALF + m * 16) * 1024 + c;
;                     f32x4 x0, x1;
;                     if (BASE_BF16) { const u32x4 v = *(const u32x4*)((const bf16_t*)base + off);
;                         x0 = (f32x4){__uint_as_float(v.x << 16), __uint_as_float(v.x & 0xffff0000u), __uint_as_float(v.y << 16), __uint_as_float(v.y & 0xffff0000u)};
;                         x1 = (f32x4){__uint_as_float(v.z << 16), __uint_as_float(v.z & 0xffff0000u), __uint_as_float(v.w << 16), __uint_as_float(v.w & 0xffff0000u)}; }
;                     else { x0 = *(const f32x4*)((const float*)base + off); x1 = *(const f32x4*)((const float*)base + off + 4); }
;                     x0 = x0 + g0 * (acc[ai][bj][m][0] + b0); x1 = x1 + g1 * (acc[ai][bj][m][1] + b1);
;                     if (OUT_BF16) { u32x4 w; w.x = pk2(x0[0], x0[1]); w.y = pk2(x0[2], x0[3]); w.z = pk2(x1[0], x1[1]); w.w = pk2(x1[2], x1[3]); *(u32x4*)((bf16_t*)out + off) = w; }
;                     else { *(f32x4*)((float*)out + off) = x0; *(f32x4*)((float*)out + off + 4) = x1; } } }
	v_lshlrev_b32_e32 v178, 16, v184
	v_and_b32_e32 v179, 0xffff0000, v184
	v_lshlrev_b32_e32 v164, 16, v185
	v_and_b32_e32 v165, 0xffff0000, v185
	v_lshlrev_b32_e32 v180, 16, v186
	v_and_b32_e32 v181, 0xffff0000, v186
	v_lshlrev_b32_e32 v166, 16, v187
	v_and_b32_e32 v167, 0xffff0000, v187
	v_pk_fma_f32 v[126:127], v[126:127], v[134:135], v[164:165]
	v_pk_fma_f32 v[124:125], v[124:125], v[132:133], v[178:179]
	v_pk_fma_f32 v[166:167], v[172:173], v[130:131], v[166:167]
	v_pk_fma_f32 v[164:165], v[174:175], v[128:129], v[180:181]
	global_store_dwordx4 v[120:121], v[124:127], off
	global_store_dwordx4 v[120:121], v[164:167], off offset:16
	s_nop 0
	s_nop 0
	v_lshlrev_b32_e32 v174, 16, v188
	v_pk_add_f32 v[166:167], v[112:113], 0 op_sel_hi:[1,0]
	v_or_b32_e32 v112, 32, v168
	v_ashrrev_i32_e32 v113, 31, v112
	v_pk_add_f32 v[164:165], v[114:115], 0 op_sel_hi:[1,0]
	v_lshlrev_b64 v[114:115], 10, v[112:113]
	v_and_b32_e32 v175, 0xffff0000, v188
	v_lshlrev_b32_e32 v124, 16, v189
	v_and_b32_e32 v125, 0xffff0000, v189
	v_lshl_add_u64 v[172:173], v[114:115], 0, v[152:153]
	v_lshl_add_u64 v[112:113], v[170:171], 2, s[26:27]
	v_lshlrev_b32_e32 v176, 16, v190
	v_and_b32_e32 v177, 0xffff0000, v190
	v_lshlrev_b32_e32 v126, 16, v191
	v_and_b32_e32 v127, 0xffff0000, v191
	v_pk_fma_f32 v[118:119], v[118:119], v[134:135], v[124:125]
	v_pk_fma_f32 v[116:117], v[116:117], v[132:133], v[174:175]
	v_lshl_add_u64 v[170:171], v[172:173], 1, s[8:9]
	v_pk_fma_f32 v[126:127], v[164:165], v[130:131], v[126:127]
	v_pk_fma_f32 v[124:125], v[166:167], v[128:129], v[176:177]
	global_store_dwordx4 v[112:113], v[116:119], off
	global_store_dwordx4 v[112:113], v[124:127], off offset:16
	s_nop 0
	s_nop 0
	v_and_b32_e32 v169, 0xffff0000, v192
	v_pk_add_f32 v[126:127], v[104:105], 0 op_sel_hi:[1,0]
	v_or_b32_e32 v104, 48, v168
	v_ashrrev_i32_e32 v105, 31, v104
	v_pk_add_f32 v[124:125], v[106:107], 0 op_sel_hi:[1,0]
	v_lshlrev_b64 v[106:107], 10, v[104:105]
	v_lshlrev_b32_e32 v168, 16, v192
	v_lshlrev_b32_e32 v116, 16, v193
	v_and_b32_e32 v117, 0xffff0000, v193
	v_lshl_add_u64 v[164:165], v[106:107], 0, v[152:153]
	v_lshl_add_u64 v[104:105], v[172:173], 2, s[26:27]
	v_lshlrev_b32_e32 v170, 16, v194
	v_and_b32_e32 v171, 0xffff0000, v194
	v_lshlrev_b32_e32 v118, 16, v195
	v_and_b32_e32 v119, 0xffff0000, v195
	v_pk_fma_f32 v[110:111], v[110:111], v[134:135], v[116:117]
	v_pk_fma_f32 v[108:109], v[108:109], v[132:133], v[168:169]
	v_lshl_add_u64 v[166:167], v[164:165], 1, s[8:9]
	v_pk_fma_f32 v[118:119], v[124:125], v[130:131], v[118:119]
	v_pk_fma_f32 v[116:117], v[126:127], v[128:129], v[170:171]
	global_store_dwordx4 v[104:105], v[108:111], off
	global_store_dwordx4 v[104:105], v[116:119], off offset:16
	s_nop 0
	s_nop 0
	v_lshlrev_b32_e32 v166, 16, v198
	v_pk_add_f32 v[116:117], v[98:99], 0 op_sel_hi:[1,0]
	v_pk_add_f32 v[118:119], v[96:97], 0 op_sel_hi:[1,0]
	v_lshl_add_u64 v[96:97], v[156:157], 0, s[14:15]
	v_lshl_add_u64 v[98:99], v[164:165], 2, s[26:27]
	v_lshlrev_b32_e32 v164, 16, v196
	v_and_b32_e32 v165, 0xffff0000, v196
	v_lshlrev_b32_e32 v108, 16, v197
	v_and_b32_e32 v109, 0xffff0000, v197
	v_lshl_add_u64 v[124:125], v[96:97], 0, v[152:153]
	v_and_b32_e32 v167, 0xffff0000, v198
	v_lshlrev_b32_e32 v110, 16, v199
	v_and_b32_e32 v111, 0xffff0000, v199
	v_pk_fma_f32 v[102:103], v[102:103], v[134:135], v[108:109]
	v_pk_fma_f32 v[100:101], v[100:101], v[132:133], v[164:165]
	v_lshl_add_u64 v[126:127], v[124:125], 1, s[8:9]
	v_pk_fma_f32 v[110:111], v[116:117], v[130:131], v[110:111]
	v_pk_fma_f32 v[108:109], v[118:119], v[128:129], v[166:167]
	global_store_dwordx4 v[98:99], v[100:103], off
	global_store_dwordx4 v[98:99], v[108:111], off offset:16
	s_nop 0
	s_nop 0
	v_lshlrev_b32_e32 v126, 16, v202
	v_pk_add_f32 v[108:109], v[90:91], 0 op_sel_hi:[1,0]
	v_pk_add_f32 v[110:111], v[88:89], 0 op_sel_hi:[1,0]
	v_lshl_add_u64 v[90:91], v[156:157], 0, s[16:17]
	v_lshl_add_u64 v[88:89], v[124:125], 2, s[26:27]
	v_lshlrev_b32_e32 v124, 16, v200
	v_and_b32_e32 v125, 0xffff0000, v200
	v_lshlrev_b32_e32 v100, 16, v201
	v_and_b32_e32 v101, 0xffff0000, v201
	v_lshl_add_u64 v[116:117], v[90:91], 0, v[152:153]
	v_and_b32_e32 v127, 0xffff0000, v202
	v_lshlrev_b32_e32 v102, 16, v203
	v_and_b32_e32 v103, 0xffff0000, v203
	v_pk_fma_f32 v[94:95], v[94:95], v[134:135], v[100:101]
	v_pk_fma_f32 v[92:93], v[92:93], v[132:133], v[124:125]
	v_lshl_add_u64 v[118:119], v[116:117], 1, s[8:9]
	v_pk_fma_f32 v[102:103], v[108:109], v[130:131], v[102:103]
	v_pk_fma_f32 v[100:101], v[110:111], v[128:129], v[126:127]
	global_store_dwordx4 v[88:89], v[92:95], off
	global_store_dwordx4 v[88:89], v[100:103], off offset:16
	s_nop 0
	s_nop 0
	v_lshlrev_b32_e32 v118, 16, v206
	v_pk_add_f32 v[100:101], v[82:83], 0 op_sel_hi:[1,0]
	v_pk_add_f32 v[102:103], v[80:81], 0 op_sel_hi:[1,0]
	v_lshl_add_u64 v[82:83], v[156:157], 0, s[18:19]
	v_lshl_add_u64 v[80:81], v[116:117], 2, s[26:27]
	v_lshlrev_b32_e32 v116, 16, v204
	v_and_b32_e32 v117, 0xffff0000, v204
	v_lshlrev_b32_e32 v92, 16, v205
	v_and_b32_e32 v93, 0xffff0000, v205
	v_lshl_add_u64 v[108:109], v[82:83], 0, v[152:153]
	v_and_b32_e32 v119, 0xffff0000, v206
	v_lshlrev_b32_e32 v94, 16, v207
	v_and_b32_e32 v95, 0xffff0000, v207
	v_pk_fma_f32 v[86:87], v[86:87], v[134:135], v[92:93]
	v_pk_fma_f32 v[84:85], v[84:85], v[132:133], v[116:117]
	v_lshl_add_u64 v[110:111], v[108:109], 1, s[8:9]
	v_pk_fma_f32 v[94:95], v[100:101], v[130:131], v[94:95]
	v_pk_fma_f32 v[92:93], v[102:103], v[128:129], v[118:119]
	global_store_dwordx4 v[80:81], v[84:87], off
	global_store_dwordx4 v[80:81], v[92:95], off offset:16
	s_nop 0
	v_pk_add_f32 v[100:101], v[72:73], 0 op_sel_hi:[1,0]
; __device__ __forceinline__ unsigned pk2(float lo, float hi) { f32x2 v = {lo, hi}; bf16x2_t b = __builtin_convertvector(v, bf16x2_t); return __builtin_bit_cast(unsigned, b); }
;     __device__ __forceinline__ void operator()(const f32x4 (&acc)[2][2][4][2], const Unit& u, int wr, int wc, int fr, int fq) const {
;     ...
;         for (int bj = 0; bj < 2; ++bj) { const int c = col0 + bj * HALF;
;             const f32x4 g0 = *(const f32x4*)(gp + c), g1 = *(const f32x4*)(gp + c + 4);
;             const f32x4 b0 = bias ? *(const f32x4*)(bias + c) : (f32x4){0.f, 0.f, 0.f, 0.f}, b1 = bias ? *(const f32x4*)(bias + c + 4) : (f32x4){0.f, 0.f, 0.f, 0.f};
; #pragma unroll
;             for (int ai = 0; ai < 2; ++ai)
; #pragma unroll
;                 for (int m = 0; m < 4; ++m) { const size_t off = (size_t)(row0 + ai * HALF + m * 16) * 1024 + c;
;                     f32x4 x0, x1;
;                     if (BASE_BF16) { const u32x4 v = *(const u32x4*)((const bf16_t*)base + off);
;                         x0 = (f32x4){__uint_as_float(v.x << 16), __uint_as_float(v.x & 0xffff0000u), __uint_as_float(v.y << 16), __uint_as_float(v.y & 0xffff0000u)};
;                         x1 = (f32x4){__uint_as_float(v.z << 16), __uint_as_float(v.z & 0xffff0000u), __uint_as_float(v.w << 16), __uint_as_float(v.w & 0xffff0000u)}; }
;                     else { x0 = *(const f32x4*)((const float*)base + off); x1 = *(const f32x4*)((const float*)base + off + 4); }
;                     x0 = x0 + g0 * (acc[ai][bj][m][0] + b0); x1 = x1 + g1 * (acc[ai][bj][m][1] + b1);
;                     if (OUT_BF16) { u32x4 w; w.x = pk2(x0[0], x0[1]); w.y = pk2(x0[2], x0[3]); w.z = pk2(x1[0], x1[1]); w.w = pk2(x1[2], x1[3]); *(u32x4*)((bf16_t*)out + off) = w; }
;                     else { *(f32x4*)((float*)out + off) = x0; *(f32x4*)((float*)out + off + 4) = x1; } } }
	v_pk_add_f32 v[92:93], v[76:77], 0 op_sel_hi:[1,0]
	v_lshl_add_u64 v[76:77], v[156:157], 0, s[20:21]
	v_lshl_add_u64 v[102:103], v[76:77], 0, v[152:153]
	v_lshl_add_u64 v[72:73], v[108:109], 2, s[26:27]
	v_lshl_add_u64 v[108:109], v[102:103], 1, s[8:9]
	s_nop 0
	v_lshlrev_b32_e32 v94, 16, v208
	v_and_b32_e32 v95, 0xffff0000, v208
	v_lshlrev_b32_e32 v84, 16, v209
	v_and_b32_e32 v85, 0xffff0000, v209
	v_lshlrev_b32_e32 v110, 16, v210
	v_and_b32_e32 v111, 0xffff0000, v210
	v_lshlrev_b32_e32 v116, 16, v211
	v_and_b32_e32 v117, 0xffff0000, v211
	v_pk_fma_f32 v[86:87], v[78:79], v[134:135], v[84:85]
	v_pk_fma_f32 v[84:85], v[92:93], v[132:133], v[94:95]
	v_pk_fma_f32 v[94:95], v[74:75], v[130:131], v[116:117]
	v_pk_fma_f32 v[92:93], v[100:101], v[128:129], v[110:111]
	global_store_dwordx4 v[72:73], v[84:87], off
	global_store_dwordx4 v[72:73], v[92:95], off offset:16
	s_nop 0
	v_or_b32_e32 v78, 0x80, v152
	v_ashrrev_i32_e32 v79, 31, v78
	v_pk_add_f32 v[94:95], v[60:61], 0 op_sel_hi:[1,0]
	v_lshl_add_u64 v[60:61], v[156:157], 0, v[78:79]
	v_pk_add_f32 v[92:93], v[62:63], 0 op_sel_hi:[1,0]
	v_lshl_add_u64 v[100:101], v[60:61], 1, s[8:9]
	v_lshl_add_u64 v[74:75], v[102:103], 2, s[26:27]
	s_nop 0
	v_lshlrev_b32_e32 v60, 16, v212
	v_and_b32_e32 v61, 0xffff0000, v212
	v_lshlrev_b32_e32 v62, 16, v213
	v_and_b32_e32 v63, 0xffff0000, v213
	v_lshlrev_b32_e32 v84, 16, v214
	v_and_b32_e32 v85, 0xffff0000, v214
	v_lshlrev_b32_e32 v86, 16, v215
	v_and_b32_e32 v87, 0xffff0000, v215
	v_pk_fma_f32 v[62:63], v[70:71], v[134:135], v[62:63]
	v_pk_fma_f32 v[60:61], v[68:69], v[132:133], v[60:61]
	v_pk_fma_f32 v[70:71], v[92:93], v[130:131], v[86:87]
	v_pk_fma_f32 v[68:69], v[94:95], v[128:129], v[84:85]
	global_store_dwordx4 v[74:75], v[60:63], off
	global_store_dwordx4 v[74:75], v[68:71], off offset:16
	s_nop 0
	s_nop 0
	global_load_dwordx4 v[68:71], v[154:155], off offset:512
	global_load_dwordx4 v[60:63], v[154:155], off offset:528
	v_pk_add_f32 v[94:95], v[56:57], 0 op_sel_hi:[1,0]
	v_lshl_add_u64 v[56:57], v[122:123], 0, v[78:79]
	v_pk_add_f32 v[92:93], v[58:59], 0 op_sel_hi:[1,0]
	v_lshl_add_u64 v[100:101], v[56:57], 1, s[8:9]
	s_nop 0
	v_lshlrev_b32_e32 v56, 16, v216
	v_and_b32_e32 v57, 0xffff0000, v216
	v_lshlrev_b32_e32 v58, 16, v217
	v_and_b32_e32 v59, 0xffff0000, v217
	v_lshlrev_b32_e32 v84, 16, v218
	v_and_b32_e32 v85, 0xffff0000, v218
	v_lshlrev_b32_e32 v86, 16, v219
	v_and_b32_e32 v87, 0xffff0000, v219
	s_waitcnt vmcnt(1)
	v_pk_fma_f32 v[58:59], v[66:67], v[70:71], v[58:59]
	v_pk_fma_f32 v[56:57], v[64:65], v[68:69], v[56:57]
	s_waitcnt vmcnt(0)
;     __device__ __forceinline__ void operator()(const f32x4 (&acc)[2][2][4][2], const Unit& u, int wr, int wc, int fr, int fq) const {
;     ...
;         for (int bj = 0; bj < 2; ++bj) { const int c = col0 + bj * HALF;
;             const f32x4 g0 = *(const f32x4*)(gp + c), g1 = *(const f32x4*)(gp + c + 4);
;             const f32x4 b0 = bias ? *(const f32x4*)(bias + c) : (f32x4){0.f, 0.f, 0.f, 0.f}, b1 = bias ? *(const f32x4*)(bias + c + 4) : (f32x4){0.f, 0.f, 0.f, 0.f};
; #pragma unroll
;             for (int ai = 0; ai < 2; ++ai)
; #pragma unroll
;                 for (int m = 0; m < 4; ++m) { const size_t off = (size_t)(row0 + ai * HALF + m * 16) * 1024 + c;
;                     f32x4 x0, x1;
;                     if (BASE_BF16) { const u32x4 v = *(const u32x4*)((const bf16_t*)base + off);
;                         x0 = (f32x4){__uint_as_float(v.x << 16), __uint_as_float(v.x & 0xffff0000u), __uint_as_float(v.y << 16), __uint_as_float(v.y & 0xffff0000u)};
;                         x1 = (f32x4){__uint_as_float(v.z << 16), __uint_as_float(v.z & 0xffff0000u), __uint_as_float(v.w << 16), __uint_as_float(v.w & 0xffff0000u)}; }
;                     else { x0 = *(const f32x4*)((const float*)base + off); x1 = *(const f32x4*)((const float*)base + off + 4); }
;                     x0 = x0 + g0 * (acc[ai][bj][m][0] + b0); x1 = x1 + g1 * (acc[ai][bj][m][1] + b1);
;                     if (OUT_BF16) { u32x4 w; w.x = pk2(x0[0], x0[1]); w.y = pk2(x0[2], x0[3]); w.z = pk2(x1[0], x1[1]); w.w = pk2(x1[2], x1[3]); *(u32x4*)((bf16_t*)out + off) = w; }
;                     else { *(f32x4*)((float*)out + off) = x0; *(f32x4*)((float*)out + off + 4) = x1; } } }
; template <class Epi, class Sched, bool ALIGN_EPI = false, bool SP2 = false>
; __device__ __forceinline__ void gemm_phase(PG8_LAS unsigned char* lds, const Gemm g, const Sched& S, const Epi& E) {
;     ...
;         if constexpr (ALIGN_EPI) { if (wr == 0) PG8_BAR; }
;         if constexpr (!Epi::AFTER_DRAIN) { E(acc, cur, wr, wc, fr, fq); S.done(cur); }
;         if (!has_next) break;
; #pragma unroll
;         for (int a = 0; a < 2; ++a)
; #pragma unroll
;             for (int b = 0; b < 2; ++b)
; #pragma unroll
;                 for (int m = 0; m < 4; ++m)
; #pragma unroll
;                     for (int n = 0; n < 2; ++n) acc[a][b][m][n] = (f32x4){0.f, 0.f, 0.f, 0.f};
;         cur = nxt; cA = nA; cB = nB; ++ui;
	v_pk_fma_f32 v[66:67], v[92:93], v[62:63], v[86:87]
	v_pk_fma_f32 v[64:65], v[94:95], v[60:61], v[84:85]
	global_store_dwordx4 v[120:121], v[56:59], off offset:512
	global_store_dwordx4 v[120:121], v[64:67], off offset:528
	s_nop 0
	s_nop 0
	v_pk_add_f32 v[66:67], v[48:49], 0 op_sel_hi:[1,0]
	v_lshl_add_u64 v[48:49], v[114:115], 0, v[78:79]
	v_pk_add_f32 v[64:65], v[50:51], 0 op_sel_hi:[1,0]
	v_lshl_add_u64 v[84:85], v[48:49], 1, s[8:9]
	s_nop 0
	v_lshlrev_b32_e32 v48, 16, v220
	v_and_b32_e32 v49, 0xffff0000, v220
	v_lshlrev_b32_e32 v50, 16, v221
	v_and_b32_e32 v51, 0xffff0000, v221
	v_lshlrev_b32_e32 v56, 16, v222
	v_and_b32_e32 v57, 0xffff0000, v222
	v_lshlrev_b32_e32 v58, 16, v223
	v_and_b32_e32 v59, 0xffff0000, v223
	v_pk_fma_f32 v[50:51], v[54:55], v[70:71], v[50:51]
	v_pk_fma_f32 v[48:49], v[52:53], v[68:69], v[48:49]
	v_pk_fma_f32 v[54:55], v[64:65], v[62:63], v[58:59]
	v_pk_fma_f32 v[52:53], v[66:67], v[60:61], v[56:57]
	global_store_dwordx4 v[112:113], v[48:51], off offset:512
	global_store_dwordx4 v[112:113], v[52:55], off offset:528
	s_nop 0
	s_nop 0
	v_pk_add_f32 v[54:55], v[40:41], 0 op_sel_hi:[1,0]
	v_lshl_add_u64 v[40:41], v[106:107], 0, v[78:79]
	v_pk_add_f32 v[52:53], v[42:43], 0 op_sel_hi:[1,0]
	v_lshl_add_u64 v[56:57], v[40:41], 1, s[8:9]
	s_nop 0
	v_lshlrev_b32_e32 v40, 16, v224
	v_and_b32_e32 v41, 0xffff0000, v224
	v_lshlrev_b32_e32 v42, 16, v225
	v_and_b32_e32 v43, 0xffff0000, v225
	v_lshlrev_b32_e32 v48, 16, v226
	v_and_b32_e32 v49, 0xffff0000, v226
	v_lshlrev_b32_e32 v50, 16, v227
	v_and_b32_e32 v51, 0xffff0000, v227
	v_pk_fma_f32 v[42:43], v[46:47], v[70:71], v[42:43]
	v_pk_fma_f32 v[40:41], v[44:45], v[68:69], v[40:41]
	v_pk_fma_f32 v[46:47], v[52:53], v[62:63], v[50:51]
	v_pk_fma_f32 v[44:45], v[54:55], v[60:61], v[48:49]
	global_store_dwordx4 v[104:105], v[40:43], off offset:512
	global_store_dwordx4 v[104:105], v[44:47], off offset:528
	s_nop 0
	s_nop 0
	v_pk_add_f32 v[46:47], v[32:33], 0 op_sel_hi:[1,0]
	v_lshl_add_u64 v[32:33], v[96:97], 0, v[78:79]
	v_pk_add_f32 v[44:45], v[34:35], 0 op_sel_hi:[1,0]
	v_lshl_add_u64 v[48:49], v[32:33], 1, s[8:9]
	s_nop 0
	v_lshlrev_b32_e32 v32, 16, v228
	v_and_b32_e32 v33, 0xffff0000, v228
	v_lshlrev_b32_e32 v34, 16, v229
	v_and_b32_e32 v35, 0xffff0000, v229
	v_lshlrev_b32_e32 v40, 16, v230
	v_and_b32_e32 v41, 0xffff0000, v230
	v_lshlrev_b32_e32 v42, 16, v231
	v_and_b32_e32 v43, 0xffff0000, v231
	v_pk_fma_f32 v[34:35], v[38:39], v[70:71], v[34:35]
	v_pk_fma_f32 v[32:33], v[36:37], v[68:69], v[32:33]
	v_pk_fma_f32 v[38:39], v[44:45], v[62:63], v[42:43]
	v_pk_fma_f32 v[36:37], v[46:47], v[60:61], v[40:41]
	global_store_dwordx4 v[98:99], v[32:35], off offset:512
	global_store_dwordx4 v[98:99], v[36:39], off offset:528
	s_nop 0
	s_nop 0
	v_pk_add_f32 v[38:39], v[24:25], 0 op_sel_hi:[1,0]
	v_lshl_add_u64 v[24:25], v[90:91], 0, v[78:79]
	v_pk_add_f32 v[36:37], v[26:27], 0 op_sel_hi:[1,0]
	v_lshl_add_u64 v[40:41], v[24:25], 1, s[8:9]
	s_nop 0
	v_lshlrev_b32_e32 v24, 16, v232
	v_and_b32_e32 v25, 0xffff0000, v232
	v_lshlrev_b32_e32 v26, 16, v233
	v_and_b32_e32 v27, 0xffff0000, v233
	v_lshlrev_b32_e32 v32, 16, v234
	v_and_b32_e32 v33, 0xffff0000, v234
	v_lshlrev_b32_e32 v34, 16, v235
	v_and_b32_e32 v35, 0xffff0000, v235
	v_pk_fma_f32 v[26:27], v[30:31], v[70:71], v[26:27]
	v_pk_fma_f32 v[24:25], v[28:29], v[68:69], v[24:25]
	v_pk_fma_f32 v[30:31], v[36:37], v[62:63], v[34:35]
	v_pk_fma_f32 v[28:29], v[38:39], v[60:61], v[32:33]
	global_store_dwordx4 v[88:89], v[24:27], off offset:512
	global_store_dwordx4 v[88:89], v[28:31], off offset:528
	s_nop 0
	s_nop 0
	v_pk_add_f32 v[30:31], v[16:17], 0 op_sel_hi:[1,0]
	v_lshl_add_u64 v[16:17], v[82:83], 0, v[78:79]
	v_pk_add_f32 v[28:29], v[18:19], 0 op_sel_hi:[1,0]
	v_lshl_add_u64 v[32:33], v[16:17], 1, s[8:9]
	s_nop 0
	v_lshlrev_b32_e32 v16, 16, v236
	v_and_b32_e32 v17, 0xffff0000, v236
	v_lshlrev_b32_e32 v18, 16, v237
	v_and_b32_e32 v19, 0xffff0000, v237
	v_lshlrev_b32_e32 v24, 16, v238
	v_and_b32_e32 v25, 0xffff0000, v238
	v_lshlrev_b32_e32 v26, 16, v239
	v_and_b32_e32 v27, 0xffff0000, v239
	v_pk_fma_f32 v[18:19], v[22:23], v[70:71], v[18:19]
	v_pk_fma_f32 v[16:17], v[20:21], v[68:69], v[16:17]
	v_pk_fma_f32 v[22:23], v[28:29], v[62:63], v[26:27]
	v_pk_fma_f32 v[20:21], v[30:31], v[60:61], v[24:25]
	global_store_dwordx4 v[80:81], v[16:19], off offset:512
	global_store_dwordx4 v[80:81], v[20:23], off offset:528
	s_nop 0
	s_nop 0
	v_pk_add_f32 v[22:23], v[8:9], 0 op_sel_hi:[1,0]
	v_lshl_add_u64 v[8:9], v[76:77], 0, v[78:79]
	v_pk_add_f32 v[20:21], v[10:11], 0 op_sel_hi:[1,0]
	v_lshl_add_u64 v[24:25], v[8:9], 1, s[8:9]
	s_nop 0
	v_lshlrev_b32_e32 v8, 16, v240
	v_and_b32_e32 v9, 0xffff0000, v240
	v_lshlrev_b32_e32 v10, 16, v241
	v_and_b32_e32 v11, 0xffff0000, v241
	v_lshlrev_b32_e32 v16, 16, v242
	v_and_b32_e32 v17, 0xffff0000, v242
	v_lshlrev_b32_e32 v18, 16, v243
	v_and_b32_e32 v19, 0xffff0000, v243
	v_pk_fma_f32 v[10:11], v[14:15], v[70:71], v[10:11]
	v_pk_fma_f32 v[8:9], v[12:13], v[68:69], v[8:9]
	v_pk_fma_f32 v[14:15], v[20:21], v[62:63], v[18:19]
	v_pk_fma_f32 v[12:13], v[22:23], v[60:61], v[16:17]
	global_store_dwordx4 v[72:73], v[8:11], off offset:512
	global_store_dwordx4 v[72:73], v[12:15], off offset:528
	s_nop 0
	s_nop 0
	v_pk_add_f32 v[12:13], v[2:3], 0 op_sel_hi:[1,0]
	v_pk_add_f32 v[14:15], v[0:1], 0 op_sel_hi:[1,0]
	s_nop 0
	v_lshlrev_b32_e32 v0, 16, v244
	v_and_b32_e32 v1, 0xffff0000, v244
	v_lshlrev_b32_e32 v2, 16, v245
	v_and_b32_e32 v3, 0xffff0000, v245
	v_lshlrev_b32_e32 v8, 16, v246
	v_and_b32_e32 v9, 0xffff0000, v246
	v_lshlrev_b32_e32 v10, 16, v247
	v_and_b32_e32 v11, 0xffff0000, v247
	v_pk_fma_f32 v[2:3], v[6:7], v[70:71], v[2:3]
	v_pk_fma_f32 v[0:1], v[4:5], v[68:69], v[0:1]
	v_pk_fma_f32 v[6:7], v[12:13], v[62:63], v[10:11]
	v_pk_fma_f32 v[4:5], v[14:15], v[60:61], v[8:9]
	global_store_dwordx4 v[74:75], v[0:3], off offset:512
	global_store_dwordx4 v[74:75], v[4:7], off offset:528
	s_cbranch_vccnz .LBB0_1405
	s_andn2_b64 vcc, exec, s[6:7]
	s_cbranch_vccnz .LBB0_1404
	s_barrier
	s_branch .LBB0_1404
